# stacked: MoBA team-0 static priority + XCD-aware MoBA pair mapping + barrier leader releases XCD before own L1 invalidate
# speedup vs baseline: 1.0002x; 1.0002x over previous
; #define PHASE_ENV unsigned char* ws = opq_ptr(p.ws); const int G = opq_int((int)gridDim.x), ngw = G * 8; (void)ws; (void)ngw
; __global__ void __launch_bounds__(512, 2) mega_fwd(Params p) {
;     ...
;         { PHASE_ENV;
;         for (int pair = blockIdx.x; pair < 256; pair += G) {
;             const int bh = pair >> 4, q16 = pair & 15;
;             moba_item(p, lds, bh >> 3, bh & 7, q16, 0);
;             moba_item(p, lds, bh >> 3, bh & 7, 15 - q16, 1);
;         }
.LBB0_422:
	s_or_b64 exec, exec, s[40:41]
	s_mov_b32 s0, s91
	s_mov_b32 s20, s78
	s_and_b64 vcc, exec, s[66:67]
	s_waitcnt lgkmcnt(0)
	s_barrier
	v_readfirstlane_b32 s100, v234
	s_nop 3
	s_bitcmp1_b32 s100, 8
	s_cbranch_scc1 .Lmoba_prio_done
	s_setprio 1
.Lmoba_prio_done:
	s_cbranch_vccnz .LBB0_499
	v_readlane_b32 s21, v255, 15
	s_mov_b32 s22, s2
	s_mov_b32 s23, s2
	s_cmpk_lg_u32 s20, 0x100
	s_cbranch_scc1 .Lmoba_noremap
	s_and_b32 s22, s2, 7
	s_lshl_b32 s22, s22, 1
	s_lshr_b32 s23, s2, 7
	s_or_b32 s22, s22, s23
	s_lshl_b32 s22, s22, 4
	s_bfe_u32 s23, s2, 0x40003
	s_or_b32 s22, s22, s23
	s_mov_b32 s23, s22
	s_xor_b32 s21, s22, 15
.Lmoba_noremap:
	s_branch .LBB0_425
.LBB0_424:
	s_add_i32 s23, s23, s20
	s_add_i32 s22, s22, s20
	s_sub_i32 s21, s21, s20
	s_cmpk_gt_i32 s23, 0xff
	s_cbranch_scc1 .LBB0_499

; __global__ void __launch_bounds__(512, 2) mega_fwd(Params p) {
;     ...
;         }
;         for (int it = blockIdx.x; it < 512; it += G) ret_kv_item(p, lds, it >> 8, (it >> 5) & 7, it & 31);
.LBB0_499:
	s_setprio 0
	v_readlane_b32 s0, v254, 26
	v_readlane_b32 s1, v254, 27
	s_andn2_b64 vcc, exec, s[0:1]
	s_mov_b32 s4, s2
	v_cndmask_b32_e64 v0, 0, 1, s[0:1]
	v_cmp_ne_u32_e64 s[6:7], 1, v0
	s_cbranch_vccnz .LBB0_501

; __global__ void __launch_bounds__(512, 2) mega_fwd(Params p) {
	.amdhsa_kernel _Z8mega_fwd6Params
		.amdhsa_group_segment_fixed_size 0
		.amdhsa_private_segment_fixed_size 0
		.amdhsa_kernarg_size 392
		.amdhsa_user_sgpr_count 2
		.amdhsa_user_sgpr_dispatch_ptr 0
		.amdhsa_user_sgpr_queue_ptr 0
		.amdhsa_user_sgpr_kernarg_segment_ptr 1
		.amdhsa_user_sgpr_dispatch_id 0
		.amdhsa_user_sgpr_kernarg_preload_length 0
		.amdhsa_user_sgpr_kernarg_preload_offset 0
		.amdhsa_user_sgpr_private_segment_size 0
		.amdhsa_uses_dynamic_stack 0
		.amdhsa_enable_private_segment 0
		.amdhsa_system_sgpr_workgroup_id_x 1
		.amdhsa_system_sgpr_workgroup_id_y 0
		.amdhsa_system_sgpr_workgroup_id_z 0
		.amdhsa_system_sgpr_workgroup_info 0
		.amdhsa_system_vgpr_workitem_id 2
		.amdhsa_next_free_vgpr 256
		.amdhsa_next_free_sgpr 102
		.amdhsa_accum_offset 256
		.amdhsa_reserve_vcc 1
		.amdhsa_float_round_mode_32 0
		.amdhsa_float_round_mode_16_64 0
		.amdhsa_float_denorm_mode_32 3
		.amdhsa_float_denorm_mode_16_64 3
		.amdhsa_dx10_clamp 1
		.amdhsa_ieee_mode 1
		.amdhsa_fp16_overflow 0
		.amdhsa_tg_split 0
		.amdhsa_exception_fp_ieee_invalid_op 0
		.amdhsa_exception_fp_denorm_src 0
		.amdhsa_exception_fp_ieee_div_zero 0
		.amdhsa_exception_fp_ieee_overflow 0
		.amdhsa_exception_fp_ieee_underflow 0
		.amdhsa_exception_fp_ieee_inexact 0
		.amdhsa_exception_int_div_zero 0
	.end_amdhsa_kernel

; __global__ void __launch_bounds__(512, 2) mega_fwd(Params p) {
amdhsa.kernels:
  - .agpr_count:     0
    .args:
      - .offset:         0
        .size:           136
        .value_kind:     by_value
      - .offset:         136
        .size:           4
        .value_kind:     hidden_block_count_x
      - .offset:         140
        .size:           4
        .value_kind:     hidden_block_count_y
      - .offset:         144
        .size:           4
        .value_kind:     hidden_block_count_z
      - .offset:         148
        .size:           2
        .value_kind:     hidden_group_size_x
      - .offset:         150
        .size:           2
        .value_kind:     hidden_group_size_y
      - .offset:         152
        .size:           2
        .value_kind:     hidden_group_size_z
      - .offset:         154
        .size:           2
        .value_kind:     hidden_remainder_x
      - .offset:         156
        .size:           2
        .value_kind:     hidden_remainder_y
      - .offset:         158
        .size:           2
        .value_kind:     hidden_remainder_z
      - .offset:         176
        .size:           8
        .value_kind:     hidden_global_offset_x
      - .offset:         184
        .size:           8
        .value_kind:     hidden_global_offset_y
      - .offset:         192
        .size:           8
        .value_kind:     hidden_global_offset_z
      - .offset:         200
        .size:           2
        .value_kind:     hidden_grid_dims
      - .offset:         224
        .size:           8
        .value_kind:     hidden_multigrid_sync_arg
      - .offset:         256
        .size:           4
        .value_kind:     hidden_dynamic_lds_size
    .group_segment_fixed_size: 0
    .kernarg_segment_align: 8
    .kernarg_segment_size: 392
    .language:       OpenCL C
    .language_version:
      - 2
      - 0
    .max_flat_workgroup_size: 512
    .name:           _Z8mega_fwd6Params
    .private_segment_fixed_size: 0
    .sgpr_count:     108
    .sgpr_spill_count: 86
    .symbol:         _Z8mega_fwd6Params.kd
    .uniform_work_group_size: 1
    .uses_dynamic_stack: false
    .vgpr_count:     256
    .vgpr_spill_count: 0
    .wavefront_size: 64
